# GEMM main loops: removed mid-burst s_setprio 0/1 pairs (16 sites)
# speedup vs baseline: 1.2398x; 1.0034x over previous
.LBB0_61:
	ds_read_b128 v[144:147], v178
	ds_read_b128 v[148:151], v178 offset:1024
	ds_read_b128 v[152:155], v178 offset:2048
	ds_read_b128 v[156:159], v178 offset:3072
	ds_read_b128 v[128:131], v179
	ds_read_b128 v[132:135], v179 offset:1024
	ds_read_b128 v[136:139], v179 offset:2048
	ds_read_b128 v[140:143], v179 offset:3072
	s_cmp_eq_u32 s54, 12
	s_cselect_b64 s[6:7], -1, 0
	s_add_u32 s4, s47, s0
	s_addc_u32 s5, s48, s1
	s_mov_b32 m0, s49
	ds_read_b128 v[190:193], v180
	ds_read_b128 v[194:197], v180 offset:1024
	ds_read_b128 v[198:201], v180 offset:2048
	ds_read_b128 v[202:205], v180 offset:3072
	ds_read_b128 v[206:209], v180 offset:4096
	ds_read_b128 v[210:213], v180 offset:5120
	ds_read_b128 v[214:217], v180 offset:6144
	ds_read_b128 v[218:221], v180 offset:7168
	global_load_lds_dwordx4 v168, s[4:5]
	s_mov_b32 m0, s50
	s_nop 0
	global_load_lds_dwordx4 v170, s[4:5]
	s_waitcnt vmcnt(8)
	s_waitcnt lgkmcnt(0)
	s_barrier
	s_setprio 1
	s_waitcnt lgkmcnt(0)
	v_mfma_f32_16x16x32_bf16 v[124:127], v[144:147], v[190:193], v[124:127]
	v_mfma_f32_16x16x32_bf16 v[120:123], v[152:155], v[190:193], v[120:123]
	v_mfma_f32_16x16x32_bf16 v[108:111], v[144:147], v[198:201], v[108:111]
	v_mfma_f32_16x16x32_bf16 v[104:107], v[152:155], v[198:201], v[104:107]
	v_mfma_f32_16x16x32_bf16 v[92:95], v[144:147], v[206:209], v[92:95]
	v_mfma_f32_16x16x32_bf16 v[88:91], v[152:155], v[206:209], v[88:91]
	v_mfma_f32_16x16x32_bf16 v[76:79], v[144:147], v[214:217], v[76:79]
	v_mfma_f32_16x16x32_bf16 v[72:75], v[152:155], v[214:217], v[72:75]
	v_mfma_f32_16x16x32_bf16 v[124:127], v[148:151], v[194:197], v[124:127]
	v_mfma_f32_16x16x32_bf16 v[120:123], v[156:159], v[194:197], v[120:123]
	v_mfma_f32_16x16x32_bf16 v[108:111], v[148:151], v[202:205], v[108:111]
	v_mfma_f32_16x16x32_bf16 v[104:107], v[156:159], v[202:205], v[104:107]
	v_mfma_f32_16x16x32_bf16 v[92:95], v[148:151], v[210:213], v[92:95]
	v_mfma_f32_16x16x32_bf16 v[88:91], v[156:159], v[210:213], v[88:91]
	v_mfma_f32_16x16x32_bf16 v[76:79], v[148:151], v[218:221], v[76:79]
	v_mfma_f32_16x16x32_bf16 v[72:75], v[156:159], v[218:221], v[72:75]
	v_mfma_f32_16x16x32_bf16 v[116:119], v[128:131], v[190:193], v[116:119]
	v_mfma_f32_16x16x32_bf16 v[112:115], v[136:139], v[190:193], v[112:115]
	v_mfma_f32_16x16x32_bf16 v[100:103], v[128:131], v[198:201], v[100:103]
	v_mfma_f32_16x16x32_bf16 v[96:99], v[136:139], v[198:201], v[96:99]
	v_mfma_f32_16x16x32_bf16 v[84:87], v[128:131], v[206:209], v[84:87]
	v_mfma_f32_16x16x32_bf16 v[80:83], v[136:139], v[206:209], v[80:83]
	v_mfma_f32_16x16x32_bf16 v[68:71], v[128:131], v[214:217], v[68:71]
	v_mfma_f32_16x16x32_bf16 v[64:67], v[136:139], v[214:217], v[64:67]
	v_mfma_f32_16x16x32_bf16 v[116:119], v[132:135], v[194:197], v[116:119]
	v_mfma_f32_16x16x32_bf16 v[112:115], v[140:143], v[194:197], v[112:115]
	v_mfma_f32_16x16x32_bf16 v[100:103], v[132:135], v[202:205], v[100:103]
	v_mfma_f32_16x16x32_bf16 v[96:99], v[140:143], v[202:205], v[96:99]
	v_mfma_f32_16x16x32_bf16 v[84:87], v[132:135], v[210:213], v[84:87]
	v_mfma_f32_16x16x32_bf16 v[80:83], v[140:143], v[210:213], v[80:83]
	v_mfma_f32_16x16x32_bf16 v[68:71], v[132:135], v[218:221], v[68:71]
	v_mfma_f32_16x16x32_bf16 v[64:67], v[140:143], v[218:221], v[64:67]
	s_setprio 0
	s_barrier
	s_and_b64 s[4:5], s[22:23], s[6:7]
	s_andn2_b64 vcc, exec, s[4:5]
	s_cbranch_vccnz .LBB0_63
	v_mov_b32_e32 v164, v174
	s_nop 0
	v_add_u32_e32 v164, s33, v164
	v_ashrrev_i32_e32 v167, 31, v164
	v_lshrrev_b32_e32 v167, 26, v167
	v_lshlrev_b32_e32 v166, 4, v164
	v_add_u32_e32 v167, v164, v167
	v_bfe_i32 v164, v164, 27, 1
	v_lshrrev_b32_e32 v164, 22, v164
	v_add_u32_e32 v164, v166, v164
	v_and_b32_e32 v164, 0xfffffc00, v164
	v_sub_u32_e32 v164, v166, v164
	v_lshrrev_b32_e32 v168, 4, v164
	v_bitop3_b32 v164, v168, v164, 32 bitop3:0x6c
	v_ashrrev_i32_e32 v169, 31, v164
	v_lshrrev_b32_e32 v169, 26, v169
	v_add_u32_e32 v169, v164, v169
	v_ashrrev_i32_e32 v170, 6, v169
	v_and_b32_e32 v169, 0xc0, v169
	v_add_u32_e32 v166, 0x2000, v166
	v_sub_u32_e32 v164, v164, v169
	v_ashrrev_i32_e32 v169, 31, v166
	v_ashrrev_i32_e32 v167, 6, v167
	v_lshrrev_b32_e32 v169, 22, v169
	v_lshlrev_b32_e32 v168, 3, v167
	v_add_u32_e32 v169, v166, v169
	v_and_b32_e32 v168, -16, v168
	v_ashrrev_i32_e32 v169, 10, v169
	v_add_u32_e32 v168, v170, v168
	v_mul_i32_i24_e32 v170, 0x400, v169
	v_sub_u32_e32 v166, v166, v170
	v_lshrrev_b32_e32 v170, 4, v166
	v_bitop3_b32 v166, v170, v166, 32 bitop3:0x6c
	v_ashrrev_i32_e32 v171, 31, v166
	v_lshrrev_b32_e32 v171, 26, v171
	v_add_u32_e32 v171, v166, v171
	v_ashrrev_i32_e32 v172, 6, v171
	v_and_b32_e32 v171, 0xc0, v171
	v_lshlrev_b32_e32 v167, 5, v167
	v_ashrrev_i16_sdwa v164, v175, sext(v164) dst_sel:DWORD dst_unused:UNUSED_PAD src0_sel:DWORD src1_sel:BYTE_0
	v_lshlrev_b32_e32 v170, 3, v169
	v_sub_u32_e32 v166, v166, v171
	v_and_b32_e32 v167, 32, v167
	v_bfe_i32 v164, v164, 0, 16
	v_and_b32_e32 v170, -16, v170
	v_lshlrev_b32_e32 v169, 5, v169
	v_ashrrev_i16_sdwa v166, v175, sext(v166) dst_sel:DWORD dst_unused:UNUSED_PAD src0_sel:DWORD src1_sel:BYTE_0
	v_add_u32_e32 v170, v172, v170
	v_and_b32_e32 v169, 32, v169
	v_bfe_i32 v166, v166, 0, 16
	v_add_u32_e32 v171, s29, v168
	v_add_lshl_u32 v164, v167, v164, 1
	v_add_u32_e32 v168, s30, v168
	v_lshl_add_u32 v167, v171, 11, v164
	v_add_u32_e32 v171, s29, v170
	v_add_lshl_u32 v169, v169, v166, 1
	v_lshl_add_u32 v164, v168, 11, v164
	v_add_u32_e32 v168, s30, v170
	v_lshl_add_u32 v166, v171, 11, v169
	v_lshl_add_u32 v170, v168, 11, v169
	v_mov_b32_e32 v171, v165
	v_mov_b64_e32 v[172:173], v[164:165]
	v_mov_b32_e32 v168, v164
	v_mov_b32_e32 v164, v167
	s_branch .LBB0_64

.LBB0_64:
	s_add_u32 s4, s0, 0x100
	s_addc_u32 s5, s1, 0
	s_and_b64 s[56:57], s[6:7], exec
	s_cselect_b32 s8, 0, s4
	s_add_u32 s55, s31, s0
	s_addc_u32 s56, s53, s1
	s_and_b64 s[0:1], s[6:7], exec
	s_cselect_b32 s1, s21, s56
	s_cselect_b32 s0, s27, s55
	s_mov_b32 m0, s35
	v_lshl_add_u64 v[222:223], s[0:1], 0, v[160:161]
	s_add_u32 s6, s0, 0x40000
	ds_read_b128 v[190:193], v180 offset:16384
	ds_read_b128 v[194:197], v180 offset:17408
	ds_read_b128 v[198:201], v180 offset:18432
	ds_read_b128 v[202:205], v180 offset:19456
	ds_read_b128 v[206:209], v180 offset:20480
	ds_read_b128 v[210:213], v180 offset:21504
	ds_read_b128 v[214:217], v180 offset:22528
	ds_read_b128 v[218:221], v180 offset:23552
	global_load_lds_dwordx4 v[222:223], off
	v_lshl_add_u64 v[224:225], s[0:1], 0, v[162:163]
	s_mov_b32 m0, s36
	s_addc_u32 s7, s1, 0
	global_load_lds_dwordx4 v[224:225], off
	v_lshl_add_u64 v[226:227], s[6:7], 0, v[160:161]
	s_mov_b32 m0, s37
	v_mov_b32_e32 v167, v165
	global_load_lds_dwordx4 v[226:227], off
	v_lshl_add_u64 v[226:227], s[6:7], 0, v[162:163]
	s_mov_b32 m0, s38
	v_lshl_add_u64 v[228:229], s[2:3], 0, v[166:167]
	global_load_lds_dwordx4 v[226:227], off
	v_lshl_add_u64 v[226:227], s[2:3], 0, v[164:165]
	v_lshl_add_u64 v[226:227], v[226:227], 0, s[8:9]
	s_mov_b32 m0, s34
	v_lshl_add_u64 v[228:229], v[228:229], 0, s[8:9]
	global_load_lds_dwordx4 v[226:227], off
	s_mov_b32 m0, s39
	s_nop 0
	global_load_lds_dwordx4 v[228:229], off
	s_waitcnt vmcnt(8)
	s_waitcnt lgkmcnt(0)
	s_barrier
	s_setprio 1
	s_waitcnt lgkmcnt(0)
	v_mfma_f32_16x16x32_bf16 v[60:63], v[144:147], v[190:193], v[60:63]
	v_mfma_f32_16x16x32_bf16 v[56:59], v[152:155], v[190:193], v[56:59]
	v_mfma_f32_16x16x32_bf16 v[44:47], v[144:147], v[198:201], v[44:47]
	v_mfma_f32_16x16x32_bf16 v[40:43], v[152:155], v[198:201], v[40:43]
	v_mfma_f32_16x16x32_bf16 v[28:31], v[144:147], v[206:209], v[28:31]
	v_mfma_f32_16x16x32_bf16 v[24:27], v[152:155], v[206:209], v[24:27]
	v_mfma_f32_16x16x32_bf16 v[12:15], v[144:147], v[214:217], v[12:15]
	v_mfma_f32_16x16x32_bf16 v[8:11], v[152:155], v[214:217], v[8:11]
	v_mfma_f32_16x16x32_bf16 v[60:63], v[148:151], v[194:197], v[60:63]
	v_mfma_f32_16x16x32_bf16 v[56:59], v[156:159], v[194:197], v[56:59]
	v_mfma_f32_16x16x32_bf16 v[44:47], v[148:151], v[202:205], v[44:47]
	v_mfma_f32_16x16x32_bf16 v[40:43], v[156:159], v[202:205], v[40:43]
	v_mfma_f32_16x16x32_bf16 v[28:31], v[148:151], v[210:213], v[28:31]
	v_mfma_f32_16x16x32_bf16 v[24:27], v[156:159], v[210:213], v[24:27]
	v_mfma_f32_16x16x32_bf16 v[12:15], v[148:151], v[218:221], v[12:15]
	v_mfma_f32_16x16x32_bf16 v[8:11], v[156:159], v[218:221], v[8:11]
	v_mfma_f32_16x16x32_bf16 v[52:55], v[128:131], v[190:193], v[52:55]
	v_mfma_f32_16x16x32_bf16 v[48:51], v[136:139], v[190:193], v[48:51]
	v_mfma_f32_16x16x32_bf16 v[36:39], v[128:131], v[198:201], v[36:39]
	v_mfma_f32_16x16x32_bf16 v[32:35], v[136:139], v[198:201], v[32:35]
	v_mfma_f32_16x16x32_bf16 v[20:23], v[128:131], v[206:209], v[20:23]
	v_mfma_f32_16x16x32_bf16 v[16:19], v[136:139], v[206:209], v[16:19]
	v_mfma_f32_16x16x32_bf16 v[4:7], v[128:131], v[214:217], v[4:7]
	v_mfma_f32_16x16x32_bf16 v[0:3], v[136:139], v[214:217], v[0:3]
	v_mfma_f32_16x16x32_bf16 v[52:55], v[132:135], v[194:197], v[52:55]
	v_mfma_f32_16x16x32_bf16 v[48:51], v[140:143], v[194:197], v[48:51]
	v_mfma_f32_16x16x32_bf16 v[36:39], v[132:135], v[202:205], v[36:39]
	v_mfma_f32_16x16x32_bf16 v[32:35], v[140:143], v[202:205], v[32:35]
	v_mfma_f32_16x16x32_bf16 v[20:23], v[132:135], v[210:213], v[20:23]
	v_mfma_f32_16x16x32_bf16 v[16:19], v[140:143], v[210:213], v[16:19]
	v_mfma_f32_16x16x32_bf16 v[4:7], v[132:135], v[218:221], v[4:7]
	v_mfma_f32_16x16x32_bf16 v[0:3], v[140:143], v[218:221], v[0:3]
	s_setprio 0
	s_barrier
	s_add_i32 s6, 0, 0x18000
	s_add_i32 s7, 0, 0x1c000
	v_add_u32_e32 v140, s6, v176
	v_add_u32_e32 v156, s7, v176
	ds_read_b128 v[128:131], v140
	ds_read_b128 v[132:135], v140 offset:1024
	ds_read_b128 v[136:139], v140 offset:2048
	ds_read_b128 v[140:143], v140 offset:3072
	ds_read_b128 v[144:147], v156
	ds_read_b128 v[148:151], v156 offset:1024
	ds_read_b128 v[152:155], v156 offset:2048
	ds_read_b128 v[156:159], v156 offset:3072
	v_lshl_add_u64 v[172:173], s[2:3], 0, v[172:173]
	s_mov_b32 m0, s40
	v_lshl_add_u64 v[172:173], v[172:173], 0, s[8:9]
	ds_read_b128 v[190:193], v180 offset:32768
	ds_read_b128 v[194:197], v180 offset:33792
	ds_read_b128 v[198:201], v180 offset:34816
	ds_read_b128 v[202:205], v180 offset:35840
	ds_read_b128 v[206:209], v180 offset:36864
	ds_read_b128 v[210:213], v180 offset:37888
	ds_read_b128 v[214:217], v180 offset:38912
	ds_read_b128 v[218:221], v180 offset:39936
	global_load_lds_dwordx4 v[172:173], off
	v_lshl_add_u64 v[172:173], s[2:3], 0, v[170:171]
	v_lshl_add_u64 v[172:173], v[172:173], 0, s[8:9]
	s_mov_b32 m0, s41
	s_nop 0
	global_load_lds_dwordx4 v[172:173], off
	s_waitcnt vmcnt(8)
	s_waitcnt lgkmcnt(0)
	s_barrier
	s_setprio 1
	s_waitcnt lgkmcnt(0)
	v_mfma_f32_16x16x32_bf16 v[124:127], v[128:131], v[190:193], v[124:127]
	v_mfma_f32_16x16x32_bf16 v[120:123], v[136:139], v[190:193], v[120:123]
	v_mfma_f32_16x16x32_bf16 v[108:111], v[128:131], v[198:201], v[108:111]
	v_mfma_f32_16x16x32_bf16 v[104:107], v[136:139], v[198:201], v[104:107]
	v_mfma_f32_16x16x32_bf16 v[92:95], v[128:131], v[206:209], v[92:95]
	v_mfma_f32_16x16x32_bf16 v[88:91], v[136:139], v[206:209], v[88:91]
	v_mfma_f32_16x16x32_bf16 v[76:79], v[128:131], v[214:217], v[76:79]
	v_mfma_f32_16x16x32_bf16 v[72:75], v[136:139], v[214:217], v[72:75]
	v_mfma_f32_16x16x32_bf16 v[124:127], v[132:135], v[194:197], v[124:127]
	v_mfma_f32_16x16x32_bf16 v[120:123], v[140:143], v[194:197], v[120:123]
	v_mfma_f32_16x16x32_bf16 v[108:111], v[132:135], v[202:205], v[108:111]
	v_mfma_f32_16x16x32_bf16 v[104:107], v[140:143], v[202:205], v[104:107]
	v_mfma_f32_16x16x32_bf16 v[92:95], v[132:135], v[210:213], v[92:95]
	v_mfma_f32_16x16x32_bf16 v[88:91], v[140:143], v[210:213], v[88:91]
	v_mfma_f32_16x16x32_bf16 v[76:79], v[132:135], v[218:221], v[76:79]
	v_mfma_f32_16x16x32_bf16 v[72:75], v[140:143], v[218:221], v[72:75]
	v_mfma_f32_16x16x32_bf16 v[116:119], v[144:147], v[190:193], v[116:119]
	v_mfma_f32_16x16x32_bf16 v[112:115], v[152:155], v[190:193], v[112:115]
	v_mfma_f32_16x16x32_bf16 v[100:103], v[144:147], v[198:201], v[100:103]
	v_mfma_f32_16x16x32_bf16 v[96:99], v[152:155], v[198:201], v[96:99]
	v_mfma_f32_16x16x32_bf16 v[84:87], v[144:147], v[206:209], v[84:87]
	v_mfma_f32_16x16x32_bf16 v[80:83], v[152:155], v[206:209], v[80:83]
	v_mfma_f32_16x16x32_bf16 v[68:71], v[144:147], v[214:217], v[68:71]
	v_mfma_f32_16x16x32_bf16 v[64:67], v[152:155], v[214:217], v[64:67]
	v_mfma_f32_16x16x32_bf16 v[116:119], v[148:151], v[194:197], v[116:119]
	v_mfma_f32_16x16x32_bf16 v[112:115], v[156:159], v[194:197], v[112:115]
	v_mfma_f32_16x16x32_bf16 v[100:103], v[148:151], v[202:205], v[100:103]
	v_mfma_f32_16x16x32_bf16 v[96:99], v[156:159], v[202:205], v[96:99]
	v_mfma_f32_16x16x32_bf16 v[84:87], v[148:151], v[210:213], v[84:87]
	v_mfma_f32_16x16x32_bf16 v[80:83], v[156:159], v[210:213], v[80:83]
	v_mfma_f32_16x16x32_bf16 v[68:71], v[148:151], v[218:221], v[68:71]
	v_mfma_f32_16x16x32_bf16 v[64:67], v[156:159], v[218:221], v[64:67]
	s_setprio 0
	s_barrier
	s_add_i32 s6, s6, s84
	v_lshl_add_u64 v[172:173], v[222:223], 0, s[14:15]
	s_mov_b32 m0, s6
	ds_read_b128 v[190:193], v180 offset:49152
	ds_read_b128 v[194:197], v180 offset:50176
	ds_read_b128 v[198:201], v180 offset:51200
	ds_read_b128 v[202:205], v180 offset:52224
	ds_read_b128 v[206:209], v180 offset:53248
	ds_read_b128 v[210:213], v180 offset:54272
	ds_read_b128 v[214:217], v180 offset:55296
	ds_read_b128 v[218:221], v180 offset:56320
	global_load_lds_dwordx4 v[172:173], off
	s_add_i32 m0, s6, 0x2000
	s_add_u32 s0, s0, 0x40080
	v_lshl_add_u64 v[172:173], v[224:225], 0, s[14:15]
	s_addc_u32 s1, s1, 0
	s_add_i32 s6, s7, s84
	global_load_lds_dwordx4 v[172:173], off
	v_lshl_add_u64 v[172:173], s[0:1], 0, v[160:161]
	s_mov_b32 m0, s6
	s_nop 0
	global_load_lds_dwordx4 v[172:173], off
	v_lshl_add_u64 v[172:173], s[0:1], 0, v[162:163]
	s_add_i32 m0, s6, 0x2000
	s_nop 0
	global_load_lds_dwordx4 v[172:173], off
	v_lshl_add_u64 v[172:173], v[226:227], 0, s[14:15]
	s_mov_b32 m0, s42
	s_nop 0
	global_load_lds_dwordx4 v[172:173], off
	v_lshl_add_u64 v[172:173], v[228:229], 0, s[14:15]
	s_mov_b32 m0, s43
	s_nop 0
	global_load_lds_dwordx4 v[172:173], off
	s_waitcnt vmcnt(8)
	s_waitcnt lgkmcnt(0)
	s_barrier
	s_setprio 1
	s_waitcnt lgkmcnt(0)
	v_mfma_f32_16x16x32_bf16 v[60:63], v[128:131], v[190:193], v[60:63]
	v_mfma_f32_16x16x32_bf16 v[56:59], v[136:139], v[190:193], v[56:59]
	v_mfma_f32_16x16x32_bf16 v[44:47], v[128:131], v[198:201], v[44:47]
	v_mfma_f32_16x16x32_bf16 v[40:43], v[136:139], v[198:201], v[40:43]
	v_mfma_f32_16x16x32_bf16 v[28:31], v[128:131], v[206:209], v[28:31]
	v_mfma_f32_16x16x32_bf16 v[24:27], v[136:139], v[206:209], v[24:27]
	v_mfma_f32_16x16x32_bf16 v[12:15], v[128:131], v[214:217], v[12:15]
	v_mfma_f32_16x16x32_bf16 v[8:11], v[136:139], v[214:217], v[8:11]
	v_mfma_f32_16x16x32_bf16 v[60:63], v[132:135], v[194:197], v[60:63]
	v_mfma_f32_16x16x32_bf16 v[56:59], v[140:143], v[194:197], v[56:59]
	v_mfma_f32_16x16x32_bf16 v[44:47], v[132:135], v[202:205], v[44:47]
	v_mfma_f32_16x16x32_bf16 v[40:43], v[140:143], v[202:205], v[40:43]
	v_mfma_f32_16x16x32_bf16 v[28:31], v[132:135], v[210:213], v[28:31]
	v_mfma_f32_16x16x32_bf16 v[24:27], v[140:143], v[210:213], v[24:27]
	v_mfma_f32_16x16x32_bf16 v[12:15], v[132:135], v[218:221], v[12:15]
	v_mfma_f32_16x16x32_bf16 v[8:11], v[140:143], v[218:221], v[8:11]
	v_mfma_f32_16x16x32_bf16 v[52:55], v[144:147], v[190:193], v[52:55]
	v_mfma_f32_16x16x32_bf16 v[48:51], v[152:155], v[190:193], v[48:51]
	v_mfma_f32_16x16x32_bf16 v[36:39], v[144:147], v[198:201], v[36:39]
	v_mfma_f32_16x16x32_bf16 v[32:35], v[152:155], v[198:201], v[32:35]
	v_mfma_f32_16x16x32_bf16 v[20:23], v[144:147], v[206:209], v[20:23]
	v_mfma_f32_16x16x32_bf16 v[16:19], v[152:155], v[206:209], v[16:19]
	v_mfma_f32_16x16x32_bf16 v[4:7], v[144:147], v[214:217], v[4:7]
	v_mfma_f32_16x16x32_bf16 v[0:3], v[152:155], v[214:217], v[0:3]
	v_mfma_f32_16x16x32_bf16 v[52:55], v[148:151], v[194:197], v[52:55]
	v_mfma_f32_16x16x32_bf16 v[48:51], v[156:159], v[194:197], v[48:51]
	v_mfma_f32_16x16x32_bf16 v[36:39], v[148:151], v[202:205], v[36:39]
	v_mfma_f32_16x16x32_bf16 v[32:35], v[156:159], v[202:205], v[32:35]
	v_mfma_f32_16x16x32_bf16 v[20:23], v[148:151], v[210:213], v[20:23]
	v_mfma_f32_16x16x32_bf16 v[16:19], v[156:159], v[210:213], v[16:19]
	v_mfma_f32_16x16x32_bf16 v[4:7], v[148:151], v[218:221], v[4:7]
	v_mfma_f32_16x16x32_bf16 v[0:3], v[156:159], v[218:221], v[0:3]
	s_setprio 0
	s_barrier
	s_add_i32 s54, s54, 2
	s_cmp_gt_u32 s54, 13
	s_cbranch_scc1 .LBB0_66
	s_mov_b64 s[0:1], s[4:5]
	s_branch .LBB0_61

.LBB0_721:
	ds_read_b128 v[144:147], v177
	ds_read_b128 v[148:151], v177 offset:1024
	ds_read_b128 v[152:155], v177 offset:2048
	ds_read_b128 v[156:159], v177 offset:3072
	ds_read_b128 v[128:131], v178
	ds_read_b128 v[132:135], v178 offset:1024
	ds_read_b128 v[136:139], v178 offset:2048
	ds_read_b128 v[140:143], v178 offset:3072
	s_cmp_eq_u32 s51, 12
	s_cselect_b64 s[24:25], -1, 0
	s_add_i32 m0, s27, 0xc000
	s_add_u32 s22, s40, s20
	s_addc_u32 s23, s41, s21
	ds_read_b128 v[180:183], v179
	ds_read_b128 v[184:187], v179 offset:1024
	ds_read_b128 v[188:191], v179 offset:2048
	ds_read_b128 v[192:195], v179 offset:3072
	ds_read_b128 v[196:199], v179 offset:4096
	ds_read_b128 v[200:203], v179 offset:5120
	ds_read_b128 v[204:207], v179 offset:6144
	ds_read_b128 v[208:211], v179 offset:7168
	global_load_lds_dwordx4 v168, s[22:23]
	s_add_i32 m0, s27, 0xe000
	s_nop 0
	global_load_lds_dwordx4 v170, s[22:23]
	s_waitcnt vmcnt(8)
	s_waitcnt lgkmcnt(0)
	s_barrier
	s_setprio 1
	s_waitcnt lgkmcnt(0)
	v_mfma_f32_16x16x32_bf16 v[124:127], v[144:147], v[180:183], v[124:127]
	v_mfma_f32_16x16x32_bf16 v[120:123], v[152:155], v[180:183], v[120:123]
	v_mfma_f32_16x16x32_bf16 v[112:115], v[144:147], v[188:191], v[112:115]
	v_mfma_f32_16x16x32_bf16 v[104:107], v[152:155], v[188:191], v[104:107]
	v_mfma_f32_16x16x32_bf16 v[96:99], v[144:147], v[196:199], v[96:99]
	v_mfma_f32_16x16x32_bf16 v[88:91], v[152:155], v[196:199], v[88:91]
	v_mfma_f32_16x16x32_bf16 v[80:83], v[144:147], v[204:207], v[80:83]
	v_mfma_f32_16x16x32_bf16 v[72:75], v[152:155], v[204:207], v[72:75]
	v_mfma_f32_16x16x32_bf16 v[124:127], v[148:151], v[184:187], v[124:127]
	v_mfma_f32_16x16x32_bf16 v[120:123], v[156:159], v[184:187], v[120:123]
	v_mfma_f32_16x16x32_bf16 v[112:115], v[148:151], v[192:195], v[112:115]
	v_mfma_f32_16x16x32_bf16 v[104:107], v[156:159], v[192:195], v[104:107]
	v_mfma_f32_16x16x32_bf16 v[96:99], v[148:151], v[200:203], v[96:99]
	v_mfma_f32_16x16x32_bf16 v[88:91], v[156:159], v[200:203], v[88:91]
	v_mfma_f32_16x16x32_bf16 v[80:83], v[148:151], v[208:211], v[80:83]
	v_mfma_f32_16x16x32_bf16 v[72:75], v[156:159], v[208:211], v[72:75]
	v_mfma_f32_16x16x32_bf16 v[116:119], v[128:131], v[180:183], v[116:119]
	v_mfma_f32_16x16x32_bf16 v[108:111], v[136:139], v[180:183], v[108:111]
	v_mfma_f32_16x16x32_bf16 v[100:103], v[128:131], v[188:191], v[100:103]
	v_mfma_f32_16x16x32_bf16 v[92:95], v[136:139], v[188:191], v[92:95]
	v_mfma_f32_16x16x32_bf16 v[84:87], v[128:131], v[196:199], v[84:87]
	v_mfma_f32_16x16x32_bf16 v[76:79], v[136:139], v[196:199], v[76:79]
	v_mfma_f32_16x16x32_bf16 v[68:71], v[128:131], v[204:207], v[68:71]
	v_mfma_f32_16x16x32_bf16 v[64:67], v[136:139], v[204:207], v[64:67]
	v_mfma_f32_16x16x32_bf16 v[116:119], v[132:135], v[184:187], v[116:119]
	v_mfma_f32_16x16x32_bf16 v[108:111], v[140:143], v[184:187], v[108:111]
	v_mfma_f32_16x16x32_bf16 v[100:103], v[132:135], v[192:195], v[100:103]
	v_mfma_f32_16x16x32_bf16 v[92:95], v[140:143], v[192:195], v[92:95]
	v_mfma_f32_16x16x32_bf16 v[84:87], v[132:135], v[200:203], v[84:87]
	v_mfma_f32_16x16x32_bf16 v[76:79], v[140:143], v[200:203], v[76:79]
	v_mfma_f32_16x16x32_bf16 v[68:71], v[132:135], v[208:211], v[68:71]
	v_mfma_f32_16x16x32_bf16 v[64:67], v[140:143], v[208:211], v[64:67]
	s_setprio 0
	s_barrier
	s_and_b64 s[22:23], s[16:17], s[24:25]
	s_andn2_b64 vcc, exec, s[22:23]
	s_cbranch_vccnz .LBB0_723
	v_mov_b32_e32 v164, v174
	s_nop 0
	v_add_u32_e32 v164, s33, v164
	v_ashrrev_i32_e32 v167, 31, v164
	v_lshrrev_b32_e32 v167, 26, v167
	v_lshlrev_b32_e32 v166, 4, v164
	v_add_u32_e32 v167, v164, v167
	v_bfe_i32 v164, v164, 27, 1
	v_lshrrev_b32_e32 v164, 22, v164
	v_add_u32_e32 v164, v166, v164
	v_and_b32_e32 v164, 0xfffffc00, v164
	v_sub_u32_e32 v164, v166, v164
	v_lshrrev_b32_e32 v168, 4, v164
	v_bitop3_b32 v164, v168, v164, 32 bitop3:0x6c
	v_ashrrev_i32_e32 v169, 31, v164
	v_lshrrev_b32_e32 v169, 26, v169
	v_add_u32_e32 v169, v164, v169
	v_ashrrev_i32_e32 v170, 6, v169
	v_and_b32_e32 v169, 0xc0, v169
	v_add_u32_e32 v166, 0x2000, v166
	v_sub_u32_e32 v164, v164, v169
	v_ashrrev_i32_e32 v169, 31, v166
	v_ashrrev_i32_e32 v167, 6, v167
	v_lshrrev_b32_e32 v169, 22, v169
	v_lshlrev_b32_e32 v168, 3, v167
	v_add_u32_e32 v169, v166, v169
	v_and_b32_e32 v168, -16, v168
	v_ashrrev_i32_e32 v169, 10, v169
	v_add_u32_e32 v168, v170, v168
	v_mul_i32_i24_e32 v170, 0x400, v169
	v_sub_u32_e32 v166, v166, v170
	v_lshrrev_b32_e32 v170, 4, v166
	v_bitop3_b32 v166, v170, v166, 32 bitop3:0x6c
	v_ashrrev_i32_e32 v171, 31, v166
	v_lshrrev_b32_e32 v171, 26, v171
	v_add_u32_e32 v171, v166, v171
	v_ashrrev_i32_e32 v172, 6, v171
	v_and_b32_e32 v171, 0xc0, v171
	v_lshlrev_b32_e32 v167, 5, v167
	v_ashrrev_i16_sdwa v164, v175, sext(v164) dst_sel:DWORD dst_unused:UNUSED_PAD src0_sel:DWORD src1_sel:BYTE_0
	v_lshlrev_b32_e32 v170, 3, v169
	v_sub_u32_e32 v166, v166, v171
	v_and_b32_e32 v167, 32, v167
	v_bfe_i32 v164, v164, 0, 16
	v_and_b32_e32 v170, -16, v170
	v_lshlrev_b32_e32 v169, 5, v169
	v_ashrrev_i16_sdwa v166, v175, sext(v166) dst_sel:DWORD dst_unused:UNUSED_PAD src0_sel:DWORD src1_sel:BYTE_0
	v_add_u32_e32 v170, v172, v170
	v_and_b32_e32 v169, 32, v169
	v_bfe_i32 v166, v166, 0, 16
	v_add_u32_e32 v171, s47, v168
	v_add_lshl_u32 v164, v167, v164, 1
	v_add_u32_e32 v168, s48, v168
	v_lshl_add_u32 v167, v171, 11, v164
	v_add_u32_e32 v171, s47, v170
	v_add_lshl_u32 v169, v169, v166, 1
	v_lshl_add_u32 v164, v168, 11, v164
	v_add_u32_e32 v168, s48, v170
	v_lshl_add_u32 v166, v171, 11, v169
	v_lshl_add_u32 v170, v168, 11, v169
	v_mov_b32_e32 v171, v165
	v_mov_b64_e32 v[172:173], v[164:165]
	v_mov_b32_e32 v168, v164
	v_mov_b32_e32 v164, v167
	s_branch .LBB0_724

.LBB0_724:
	s_add_u32 s22, s20, 0x100
	s_addc_u32 s23, s21, 0
	s_and_b64 s[52:53], s[24:25], exec
	s_cselect_b32 s0, 0, s22
	s_add_u32 s52, s49, s20
	s_addc_u32 s53, s50, s21
	s_and_b64 s[20:21], s[24:25], exec
	s_cselect_b32 s21, s15, s53
	s_cselect_b32 s20, s46, s52
	s_mov_b32 m0, s28
	v_lshl_add_u64 v[212:213], s[20:21], 0, v[162:163]
	s_add_u32 s24, s20, 0x40000
	ds_read_b128 v[180:183], v179 offset:16384
	ds_read_b128 v[184:187], v179 offset:17408
	ds_read_b128 v[188:191], v179 offset:18432
	ds_read_b128 v[192:195], v179 offset:19456
	ds_read_b128 v[196:199], v179 offset:20480
	ds_read_b128 v[200:203], v179 offset:21504
	ds_read_b128 v[204:207], v179 offset:22528
	ds_read_b128 v[208:211], v179 offset:23552
	global_load_lds_dwordx4 v[212:213], off
	v_lshl_add_u64 v[214:215], s[20:21], 0, v[160:161]
	s_mov_b32 m0, s29
	s_addc_u32 s25, s21, 0
	global_load_lds_dwordx4 v[214:215], off
	v_lshl_add_u64 v[216:217], s[24:25], 0, v[162:163]
	s_mov_b32 m0, s30
	v_mov_b32_e32 v167, v165
	global_load_lds_dwordx4 v[216:217], off
	v_lshl_add_u64 v[216:217], s[24:25], 0, v[160:161]
	s_mov_b32 m0, s31
	v_lshl_add_u64 v[218:219], s[2:3], 0, v[166:167]
	global_load_lds_dwordx4 v[216:217], off
	v_lshl_add_u64 v[216:217], s[2:3], 0, v[164:165]
	v_lshl_add_u64 v[216:217], v[216:217], 0, s[0:1]
	s_mov_b32 m0, s27
	v_lshl_add_u64 v[218:219], v[218:219], 0, s[0:1]
	global_load_lds_dwordx4 v[216:217], off
	s_mov_b32 m0, s34
	s_nop 0
	global_load_lds_dwordx4 v[218:219], off
	s_waitcnt vmcnt(8)
	s_waitcnt lgkmcnt(0)
	s_barrier
	s_setprio 1
	s_waitcnt lgkmcnt(0)
	v_mfma_f32_16x16x32_bf16 v[60:63], v[144:147], v[180:183], v[60:63]
	v_mfma_f32_16x16x32_bf16 v[56:59], v[152:155], v[180:183], v[56:59]
	v_mfma_f32_16x16x32_bf16 v[48:51], v[144:147], v[188:191], v[48:51]
	v_mfma_f32_16x16x32_bf16 v[40:43], v[152:155], v[188:191], v[40:43]
	v_mfma_f32_16x16x32_bf16 v[32:35], v[144:147], v[196:199], v[32:35]
	v_mfma_f32_16x16x32_bf16 v[24:27], v[152:155], v[196:199], v[24:27]
	v_mfma_f32_16x16x32_bf16 v[16:19], v[144:147], v[204:207], v[16:19]
	v_mfma_f32_16x16x32_bf16 v[8:11], v[152:155], v[204:207], v[8:11]
	v_mfma_f32_16x16x32_bf16 v[60:63], v[148:151], v[184:187], v[60:63]
	v_mfma_f32_16x16x32_bf16 v[56:59], v[156:159], v[184:187], v[56:59]
	v_mfma_f32_16x16x32_bf16 v[48:51], v[148:151], v[192:195], v[48:51]
	v_mfma_f32_16x16x32_bf16 v[40:43], v[156:159], v[192:195], v[40:43]
	v_mfma_f32_16x16x32_bf16 v[32:35], v[148:151], v[200:203], v[32:35]
	v_mfma_f32_16x16x32_bf16 v[24:27], v[156:159], v[200:203], v[24:27]
	v_mfma_f32_16x16x32_bf16 v[16:19], v[148:151], v[208:211], v[16:19]
	v_mfma_f32_16x16x32_bf16 v[8:11], v[156:159], v[208:211], v[8:11]
	v_mfma_f32_16x16x32_bf16 v[52:55], v[128:131], v[180:183], v[52:55]
	v_mfma_f32_16x16x32_bf16 v[44:47], v[136:139], v[180:183], v[44:47]
	v_mfma_f32_16x16x32_bf16 v[36:39], v[128:131], v[188:191], v[36:39]
	v_mfma_f32_16x16x32_bf16 v[28:31], v[136:139], v[188:191], v[28:31]
	v_mfma_f32_16x16x32_bf16 v[20:23], v[128:131], v[196:199], v[20:23]
	v_mfma_f32_16x16x32_bf16 v[12:15], v[136:139], v[196:199], v[12:15]
	v_mfma_f32_16x16x32_bf16 v[4:7], v[128:131], v[204:207], v[4:7]
	v_mfma_f32_16x16x32_bf16 v[0:3], v[136:139], v[204:207], v[0:3]
	v_mfma_f32_16x16x32_bf16 v[52:55], v[132:135], v[184:187], v[52:55]
	v_mfma_f32_16x16x32_bf16 v[44:47], v[140:143], v[184:187], v[44:47]
	v_mfma_f32_16x16x32_bf16 v[36:39], v[132:135], v[192:195], v[36:39]
	v_mfma_f32_16x16x32_bf16 v[28:31], v[140:143], v[192:195], v[28:31]
	v_mfma_f32_16x16x32_bf16 v[20:23], v[132:135], v[200:203], v[20:23]
	v_mfma_f32_16x16x32_bf16 v[12:15], v[140:143], v[200:203], v[12:15]
	v_mfma_f32_16x16x32_bf16 v[4:7], v[132:135], v[208:211], v[4:7]
	v_mfma_f32_16x16x32_bf16 v[0:3], v[140:143], v[208:211], v[0:3]
	s_setprio 0
	s_barrier
	s_add_i32 s24, 0, 0x18000
	s_add_i32 s25, 0, 0x1c000
	v_add_u32_e32 v140, s24, v176
	v_add_u32_e32 v156, s25, v176
	ds_read_b128 v[128:131], v140
	ds_read_b128 v[132:135], v140 offset:1024
	ds_read_b128 v[136:139], v140 offset:2048
	ds_read_b128 v[140:143], v140 offset:3072
	ds_read_b128 v[144:147], v156
	ds_read_b128 v[148:151], v156 offset:1024
	ds_read_b128 v[152:155], v156 offset:2048
	ds_read_b128 v[156:159], v156 offset:3072
	v_lshl_add_u64 v[172:173], s[2:3], 0, v[172:173]
	s_mov_b32 m0, s35
	v_lshl_add_u64 v[172:173], v[172:173], 0, s[0:1]
	ds_read_b128 v[180:183], v179 offset:32768
	ds_read_b128 v[184:187], v179 offset:33792
	ds_read_b128 v[188:191], v179 offset:34816
	ds_read_b128 v[192:195], v179 offset:35840
	ds_read_b128 v[196:199], v179 offset:36864
	ds_read_b128 v[200:203], v179 offset:37888
	ds_read_b128 v[204:207], v179 offset:38912
	ds_read_b128 v[208:211], v179 offset:39936
	global_load_lds_dwordx4 v[172:173], off
	v_lshl_add_u64 v[172:173], s[2:3], 0, v[170:171]
	v_lshl_add_u64 v[172:173], v[172:173], 0, s[0:1]
	s_mov_b32 m0, s36
	s_nop 0
	global_load_lds_dwordx4 v[172:173], off
	s_waitcnt vmcnt(8)
	s_waitcnt lgkmcnt(0)
	s_barrier
	s_setprio 1
	s_waitcnt lgkmcnt(0)
	v_mfma_f32_16x16x32_bf16 v[124:127], v[128:131], v[180:183], v[124:127]
	v_mfma_f32_16x16x32_bf16 v[120:123], v[136:139], v[180:183], v[120:123]
	v_mfma_f32_16x16x32_bf16 v[112:115], v[128:131], v[188:191], v[112:115]
	v_mfma_f32_16x16x32_bf16 v[104:107], v[136:139], v[188:191], v[104:107]
	v_mfma_f32_16x16x32_bf16 v[96:99], v[128:131], v[196:199], v[96:99]
	v_mfma_f32_16x16x32_bf16 v[88:91], v[136:139], v[196:199], v[88:91]
	v_mfma_f32_16x16x32_bf16 v[80:83], v[128:131], v[204:207], v[80:83]
	v_mfma_f32_16x16x32_bf16 v[72:75], v[136:139], v[204:207], v[72:75]
	v_mfma_f32_16x16x32_bf16 v[124:127], v[132:135], v[184:187], v[124:127]
	v_mfma_f32_16x16x32_bf16 v[120:123], v[140:143], v[184:187], v[120:123]
	v_mfma_f32_16x16x32_bf16 v[112:115], v[132:135], v[192:195], v[112:115]
	v_mfma_f32_16x16x32_bf16 v[104:107], v[140:143], v[192:195], v[104:107]
	v_mfma_f32_16x16x32_bf16 v[96:99], v[132:135], v[200:203], v[96:99]
	v_mfma_f32_16x16x32_bf16 v[88:91], v[140:143], v[200:203], v[88:91]
	v_mfma_f32_16x16x32_bf16 v[80:83], v[132:135], v[208:211], v[80:83]
	v_mfma_f32_16x16x32_bf16 v[72:75], v[140:143], v[208:211], v[72:75]
	v_mfma_f32_16x16x32_bf16 v[116:119], v[144:147], v[180:183], v[116:119]
	v_mfma_f32_16x16x32_bf16 v[108:111], v[152:155], v[180:183], v[108:111]
	v_mfma_f32_16x16x32_bf16 v[100:103], v[144:147], v[188:191], v[100:103]
	v_mfma_f32_16x16x32_bf16 v[92:95], v[152:155], v[188:191], v[92:95]
	v_mfma_f32_16x16x32_bf16 v[84:87], v[144:147], v[196:199], v[84:87]
	v_mfma_f32_16x16x32_bf16 v[76:79], v[152:155], v[196:199], v[76:79]
	v_mfma_f32_16x16x32_bf16 v[68:71], v[144:147], v[204:207], v[68:71]
	v_mfma_f32_16x16x32_bf16 v[64:67], v[152:155], v[204:207], v[64:67]
	v_mfma_f32_16x16x32_bf16 v[116:119], v[148:151], v[184:187], v[116:119]
	v_mfma_f32_16x16x32_bf16 v[108:111], v[156:159], v[184:187], v[108:111]
	v_mfma_f32_16x16x32_bf16 v[100:103], v[148:151], v[192:195], v[100:103]
	v_mfma_f32_16x16x32_bf16 v[92:95], v[156:159], v[192:195], v[92:95]
	v_mfma_f32_16x16x32_bf16 v[84:87], v[148:151], v[200:203], v[84:87]
	v_mfma_f32_16x16x32_bf16 v[76:79], v[156:159], v[200:203], v[76:79]
	v_mfma_f32_16x16x32_bf16 v[68:71], v[148:151], v[208:211], v[68:71]
	v_mfma_f32_16x16x32_bf16 v[64:67], v[156:159], v[208:211], v[64:67]
	s_setprio 0
	s_barrier
	s_add_i32 s0, s24, s84
	v_lshl_add_u64 v[172:173], v[212:213], 0, s[6:7]
	s_mov_b32 m0, s0
	ds_read_b128 v[180:183], v179 offset:49152
	ds_read_b128 v[184:187], v179 offset:50176
	ds_read_b128 v[188:191], v179 offset:51200
	ds_read_b128 v[192:195], v179 offset:52224
	ds_read_b128 v[196:199], v179 offset:53248
	ds_read_b128 v[200:203], v179 offset:54272
	ds_read_b128 v[204:207], v179 offset:55296
	ds_read_b128 v[208:211], v179 offset:56320
	global_load_lds_dwordx4 v[172:173], off
	s_add_i32 m0, s0, 0x2000
	s_add_u32 s20, s20, 0x40080
	v_lshl_add_u64 v[172:173], v[214:215], 0, s[6:7]
	s_addc_u32 s21, s21, 0
	s_add_i32 s0, s25, s84
	global_load_lds_dwordx4 v[172:173], off
	v_lshl_add_u64 v[172:173], s[20:21], 0, v[162:163]
	s_mov_b32 m0, s0
	s_nop 0
	global_load_lds_dwordx4 v[172:173], off
	v_lshl_add_u64 v[172:173], s[20:21], 0, v[160:161]
	s_add_i32 m0, s0, 0x2000
	s_nop 0
	global_load_lds_dwordx4 v[172:173], off
	v_lshl_add_u64 v[172:173], v[216:217], 0, s[6:7]
	s_mov_b32 m0, s37
	s_nop 0
	global_load_lds_dwordx4 v[172:173], off
	v_lshl_add_u64 v[172:173], v[218:219], 0, s[6:7]
	s_mov_b32 m0, s38
	s_nop 0
	global_load_lds_dwordx4 v[172:173], off
	s_waitcnt vmcnt(8)
	s_waitcnt lgkmcnt(0)
	s_barrier
	s_setprio 1
	s_waitcnt lgkmcnt(0)
	v_mfma_f32_16x16x32_bf16 v[60:63], v[128:131], v[180:183], v[60:63]
	v_mfma_f32_16x16x32_bf16 v[56:59], v[136:139], v[180:183], v[56:59]
	v_mfma_f32_16x16x32_bf16 v[48:51], v[128:131], v[188:191], v[48:51]
	v_mfma_f32_16x16x32_bf16 v[40:43], v[136:139], v[188:191], v[40:43]
	v_mfma_f32_16x16x32_bf16 v[32:35], v[128:131], v[196:199], v[32:35]
	v_mfma_f32_16x16x32_bf16 v[24:27], v[136:139], v[196:199], v[24:27]
	v_mfma_f32_16x16x32_bf16 v[16:19], v[128:131], v[204:207], v[16:19]
	v_mfma_f32_16x16x32_bf16 v[8:11], v[136:139], v[204:207], v[8:11]
	v_mfma_f32_16x16x32_bf16 v[60:63], v[132:135], v[184:187], v[60:63]
	v_mfma_f32_16x16x32_bf16 v[56:59], v[140:143], v[184:187], v[56:59]
	v_mfma_f32_16x16x32_bf16 v[48:51], v[132:135], v[192:195], v[48:51]
	v_mfma_f32_16x16x32_bf16 v[40:43], v[140:143], v[192:195], v[40:43]
	v_mfma_f32_16x16x32_bf16 v[32:35], v[132:135], v[200:203], v[32:35]
	v_mfma_f32_16x16x32_bf16 v[24:27], v[140:143], v[200:203], v[24:27]
	v_mfma_f32_16x16x32_bf16 v[16:19], v[132:135], v[208:211], v[16:19]
	v_mfma_f32_16x16x32_bf16 v[8:11], v[140:143], v[208:211], v[8:11]
	v_mfma_f32_16x16x32_bf16 v[52:55], v[144:147], v[180:183], v[52:55]
	v_mfma_f32_16x16x32_bf16 v[44:47], v[152:155], v[180:183], v[44:47]
	v_mfma_f32_16x16x32_bf16 v[36:39], v[144:147], v[188:191], v[36:39]
	v_mfma_f32_16x16x32_bf16 v[28:31], v[152:155], v[188:191], v[28:31]
	v_mfma_f32_16x16x32_bf16 v[20:23], v[144:147], v[196:199], v[20:23]
	v_mfma_f32_16x16x32_bf16 v[12:15], v[152:155], v[196:199], v[12:15]
	v_mfma_f32_16x16x32_bf16 v[4:7], v[144:147], v[204:207], v[4:7]
	v_mfma_f32_16x16x32_bf16 v[0:3], v[152:155], v[204:207], v[0:3]
	v_mfma_f32_16x16x32_bf16 v[52:55], v[148:151], v[184:187], v[52:55]
	v_mfma_f32_16x16x32_bf16 v[44:47], v[156:159], v[184:187], v[44:47]
	v_mfma_f32_16x16x32_bf16 v[36:39], v[148:151], v[192:195], v[36:39]
	v_mfma_f32_16x16x32_bf16 v[28:31], v[156:159], v[192:195], v[28:31]
	v_mfma_f32_16x16x32_bf16 v[20:23], v[148:151], v[200:203], v[20:23]
	v_mfma_f32_16x16x32_bf16 v[12:15], v[156:159], v[200:203], v[12:15]
	v_mfma_f32_16x16x32_bf16 v[4:7], v[148:151], v[208:211], v[4:7]
	v_mfma_f32_16x16x32_bf16 v[0:3], v[156:159], v[208:211], v[0:3]
	s_setprio 0
	s_barrier
	s_add_i32 s51, s51, 2
	s_cmp_gt_u32 s51, 13
	s_cbranch_scc1 .LBB0_726
	s_mov_b64 s[20:21], s[22:23]
	s_branch .LBB0_721

.LBB0_1248:
	ds_read_b128 v[16:19], v177
	ds_read_b128 v[20:23], v177 offset:1024
	ds_read_b128 v[24:27], v177 offset:2048
	ds_read_b128 v[28:31], v177 offset:3072
	ds_read_b128 v[0:3], v178
	ds_read_b128 v[4:7], v178 offset:1024
	ds_read_b128 v[8:11], v178 offset:2048
	ds_read_b128 v[12:15], v178 offset:3072
	s_cmp_eq_u32 s57, 4
	s_cselect_b64 s[26:27], -1, 0
	s_add_u32 s24, s40, s22
	s_addc_u32 s25, s41, s23
	s_mov_b32 m0, s43
	ds_read_b128 v[180:183], v179
	ds_read_b128 v[184:187], v179 offset:1024
	ds_read_b128 v[188:191], v179 offset:2048
	ds_read_b128 v[192:195], v179 offset:3072
	ds_read_b128 v[196:199], v179 offset:4096
	ds_read_b128 v[200:203], v179 offset:5120
	ds_read_b128 v[204:207], v179 offset:6144
	ds_read_b128 v[208:211], v179 offset:7168
	global_load_lds_dwordx4 v168, s[24:25]
	s_mov_b32 m0, s44
	s_nop 0
	global_load_lds_dwordx4 v166, s[24:25]
	s_waitcnt vmcnt(8)
	s_waitcnt lgkmcnt(0)
	s_barrier
	s_setprio 1
	s_waitcnt lgkmcnt(0)
	v_mfma_f32_16x16x128_f8f6f4 v[156:159], v[16:23], v[180:187], v[156:159]
	v_mfma_f32_16x16x128_f8f6f4 v[152:155], v[24:31], v[180:187], v[152:155]
	v_mfma_f32_16x16x128_f8f6f4 v[140:143], v[16:23], v[188:195], v[140:143]
	v_mfma_f32_16x16x128_f8f6f4 v[136:139], v[24:31], v[188:195], v[136:139]
	v_mfma_f32_16x16x128_f8f6f4 v[124:127], v[16:23], v[196:203], v[124:127]
	v_mfma_f32_16x16x128_f8f6f4 v[120:123], v[24:31], v[196:203], v[120:123]
	v_mfma_f32_16x16x128_f8f6f4 v[108:111], v[16:23], v[204:211], v[108:111]
	v_mfma_f32_16x16x128_f8f6f4 v[104:107], v[24:31], v[204:211], v[104:107]
	v_mfma_f32_16x16x128_f8f6f4 v[148:151], v[0:7], v[180:187], v[148:151]
	v_mfma_f32_16x16x128_f8f6f4 v[144:147], v[8:15], v[180:187], v[144:147]
	v_mfma_f32_16x16x128_f8f6f4 v[132:135], v[0:7], v[188:195], v[132:135]
	v_mfma_f32_16x16x128_f8f6f4 v[128:131], v[8:15], v[188:195], v[128:131]
	v_mfma_f32_16x16x128_f8f6f4 v[116:119], v[0:7], v[196:203], v[116:119]
	v_mfma_f32_16x16x128_f8f6f4 v[112:115], v[8:15], v[196:203], v[112:115]
	v_mfma_f32_16x16x128_f8f6f4 v[100:103], v[0:7], v[204:211], v[100:103]
	v_mfma_f32_16x16x128_f8f6f4 v[96:99], v[8:15], v[204:211], v[96:99]
	s_setprio 0
	s_barrier
	s_and_b64 s[24:25], s[18:19], s[26:27]
	s_andn2_b64 vcc, exec, s[24:25]
	s_cbranch_vccnz .LBB0_1250
	v_mov_b32_e32 v164, v174
	s_nop 0
	v_add_u32_e32 v164, s33, v164
	v_ashrrev_i32_e32 v167, 31, v164
	v_lshrrev_b32_e32 v167, 26, v167
	v_lshlrev_b32_e32 v166, 4, v164
	v_add_u32_e32 v167, v164, v167
	v_bfe_i32 v164, v164, 27, 1
	v_lshrrev_b32_e32 v164, 22, v164
	v_add_u32_e32 v164, v166, v164
	v_and_b32_e32 v164, 0xfffffc00, v164
	v_sub_u32_e32 v164, v166, v164
	v_ashrrev_i32_e32 v180, 6, v167
	v_lshrrev_b32_e32 v167, 4, v164
	v_bitop3_b32 v164, v167, v164, 32 bitop3:0x6c
	v_ashrrev_i32_e32 v168, 31, v164
	v_lshrrev_b32_e32 v168, 26, v168
	v_lshlrev_b32_e32 v167, 3, v180
	v_add_u32_e32 v181, v164, v168
	v_and_b32_e32 v167, -16, v167
	v_ashrrev_i32_e32 v168, 6, v181
	v_add_u32_e32 v166, 0x2000, v166
	v_add_u32_e32 v170, v168, v167
	v_ashrrev_i32_e32 v167, 31, v166
	v_lshrrev_b32_e32 v167, 22, v167
	v_add_u32_e32 v167, v166, v167
	v_ashrrev_i32_e32 v182, 10, v167
	v_mul_i32_i24_e32 v167, 0x400, v182
	v_sub_u32_e32 v166, v166, v167
	v_lshrrev_b32_e32 v167, 4, v166
	v_bitop3_b32 v183, v167, v166, 32 bitop3:0x6c
	v_ashrrev_i32_e32 v167, 31, v183
	v_lshrrev_b32_e32 v167, 26, v167
	v_lshlrev_b32_e32 v166, 3, v182
	v_add_u32_e32 v184, v183, v167
	v_and_b32_e32 v166, -16, v166
	v_ashrrev_i32_e32 v167, 6, v184
	v_add_u32_e32 v172, v167, v166
	v_add_u32_e32 v166, s51, v170
	v_add_u32_e32 v168, s51, v172
	v_add_u32_e32 v170, s52, v170
	v_ashrrev_i32_e32 v167, 31, v166
	v_ashrrev_i32_e32 v169, 31, v168
	v_ashrrev_i32_e32 v171, 31, v170
	v_add_u32_e32 v172, s52, v172
	v_lshl_add_u64 v[166:167], v[166:167], 2, s[0:1]
	v_lshl_add_u64 v[168:169], v[168:169], 2, s[0:1]
	v_lshl_add_u64 v[170:171], v[170:171], 2, s[0:1]
	v_ashrrev_i32_e32 v173, 31, v172
	v_lshl_add_u64 v[172:173], v[172:173], 2, s[0:1]
	global_load_dword v166, v[166:167], off
	s_nop 0
	global_load_dword v168, v[168:169], off
	s_nop 0
	global_load_dword v169, v[170:171], off
	s_nop 0
	global_load_dword v171, v[172:173], off
	v_and_b32_e32 v173, 0xc0, v181
	v_sub_u32_e32 v164, v164, v173
	v_lshlrev_b32_e32 v170, 5, v180
	v_ashrrev_i16_sdwa v164, v175, sext(v164) dst_sel:DWORD dst_unused:UNUSED_PAD src0_sel:DWORD src1_sel:BYTE_0
	v_and_b32_e32 v173, 0xc0, v184
	v_and_b32_e32 v170, 32, v170
	v_bfe_i32 v164, v164, 0, 16
	v_sub_u32_e32 v173, v183, v173
	v_lshlrev_b32_e32 v172, 5, v182
	v_add_lshl_u32 v164, v170, v164, 1
	v_ashrrev_i16_sdwa v170, v175, sext(v173) dst_sel:DWORD dst_unused:UNUSED_PAD src0_sel:DWORD src1_sel:BYTE_0
	v_and_b32_e32 v172, 32, v172
	v_bfe_i32 v170, v170, 0, 16
	v_add_lshl_u32 v172, v172, v170, 1
	v_mov_b32_e32 v167, v165
	s_waitcnt vmcnt(0)
	v_lshl_add_u32 v180, v166, 10, v164
	v_lshl_add_u32 v170, v168, 10, v172
	v_lshl_add_u32 v164, v169, 10, v164
	v_lshl_add_u32 v166, v171, 10, v172
	v_mov_b64_e32 v[172:173], v[164:165]
	v_mov_b32_e32 v168, v164
	v_mov_b32_e32 v164, v180
	s_branch .LBB0_1251

.LBB0_1251:
	s_add_u32 s24, s22, 0x100
	s_addc_u32 s25, s23, 0
	s_and_b64 s[70:71], s[26:27], exec
	s_cselect_b32 s6, 0, s24
	s_add_u32 s70, s53, s22
	s_addc_u32 s71, s56, s23
	s_and_b64 s[22:23], s[26:27], exec
	s_cselect_b32 s23, s17, s71
	s_cselect_b32 s22, s50, s70
	s_mov_b32 m0, s29
	v_lshl_add_u64 v[232:233], s[22:23], 0, v[162:163]
	s_add_u32 s26, s22, 0x20000
	ds_read_b128 v[180:183], v179 offset:16384
	ds_read_b128 v[184:187], v179 offset:17408
	ds_read_b128 v[188:191], v179 offset:18432
	ds_read_b128 v[192:195], v179 offset:19456
	ds_read_b128 v[196:199], v179 offset:20480
	ds_read_b128 v[200:203], v179 offset:21504
	ds_read_b128 v[204:207], v179 offset:22528
	ds_read_b128 v[208:211], v179 offset:23552
	global_load_lds_dwordx4 v[232:233], off
	v_lshl_add_u64 v[234:235], s[22:23], 0, v[160:161]
	s_mov_b32 m0, s30
	s_addc_u32 s27, s23, 0
	global_load_lds_dwordx4 v[234:235], off
	v_lshl_add_u64 v[212:213], s[26:27], 0, v[162:163]
	s_mov_b32 m0, s31
	v_mov_b32_e32 v171, v165
	global_load_lds_dwordx4 v[212:213], off
	v_lshl_add_u64 v[212:213], s[26:27], 0, v[160:161]
	s_mov_b32 m0, s34
	s_nop 0
	global_load_lds_dwordx4 v[212:213], off
	v_lshl_add_u64 v[212:213], s[4:5], 0, v[164:165]
	v_lshl_add_u64 v[236:237], v[212:213], 0, s[6:7]
	s_mov_b32 m0, s28
	v_lshl_add_u64 v[212:213], s[4:5], 0, v[170:171]
	global_load_lds_dwordx4 v[236:237], off
	v_lshl_add_u64 v[238:239], v[212:213], 0, s[6:7]
	s_mov_b32 m0, s35
	s_nop 0
	global_load_lds_dwordx4 v[238:239], off
	s_waitcnt vmcnt(8)
	s_waitcnt lgkmcnt(0)
	s_barrier
	s_setprio 1
	s_waitcnt lgkmcnt(0)
	v_mfma_f32_16x16x128_f8f6f4 v[92:95], v[16:23], v[180:187], v[92:95]
	v_mfma_f32_16x16x128_f8f6f4 v[88:91], v[24:31], v[180:187], v[88:91]
	v_mfma_f32_16x16x128_f8f6f4 v[76:79], v[16:23], v[188:195], v[76:79]
	v_mfma_f32_16x16x128_f8f6f4 v[72:75], v[24:31], v[188:195], v[72:75]
	v_mfma_f32_16x16x128_f8f6f4 v[212:215], v[16:23], v[196:203], v[60:63]
	v_mfma_f32_16x16x128_f8f6f4 v[216:219], v[24:31], v[196:203], v[56:59]
	v_mfma_f32_16x16x128_f8f6f4 v[220:223], v[16:23], v[204:211], v[44:47]
	v_mfma_f32_16x16x128_f8f6f4 v[224:227], v[24:31], v[204:211], v[40:43]
	v_mfma_f32_16x16x128_f8f6f4 v[84:87], v[0:7], v[180:187], v[84:87]
	v_mfma_f32_16x16x128_f8f6f4 v[80:83], v[8:15], v[180:187], v[80:83]
	v_mfma_f32_16x16x128_f8f6f4 v[68:71], v[0:7], v[188:195], v[68:71]
	v_mfma_f32_16x16x128_f8f6f4 v[64:67], v[8:15], v[188:195], v[64:67]
	v_mfma_f32_16x16x128_f8f6f4 v[228:231], v[0:7], v[196:203], v[52:55]
	v_mfma_f32_16x16x128_f8f6f4 v[196:199], v[8:15], v[196:203], v[48:51]
	v_mfma_f32_16x16x128_f8f6f4 v[200:203], v[0:7], v[204:211], v[36:39]
	v_mfma_f32_16x16x128_f8f6f4 v[204:207], v[8:15], v[204:211], v[32:35]
	s_setprio 0
	s_barrier
	s_add_i32 s26, 0, 0x18000
	s_add_i32 s27, 0, 0x1c000
	v_add_u32_e32 v12, s26, v176
	v_add_u32_e32 v28, s27, v176
	ds_read_b128 v[0:3], v12
	ds_read_b128 v[4:7], v12 offset:1024
	ds_read_b128 v[8:11], v12 offset:2048
	ds_read_b128 v[12:15], v12 offset:3072
	ds_read_b128 v[16:19], v28
	ds_read_b128 v[20:23], v28 offset:1024
	ds_read_b128 v[24:27], v28 offset:2048
	ds_read_b128 v[28:31], v28 offset:3072
	v_lshl_add_u64 v[172:173], s[4:5], 0, v[172:173]
	s_mov_b32 m0, s36
	v_lshl_add_u64 v[172:173], v[172:173], 0, s[6:7]
	ds_read_b128 v[32:35], v179 offset:32768
	ds_read_b128 v[36:39], v179 offset:33792
	ds_read_b128 v[40:43], v179 offset:34816
	ds_read_b128 v[44:47], v179 offset:35840
	ds_read_b128 v[48:51], v179 offset:36864
	ds_read_b128 v[52:55], v179 offset:37888
	ds_read_b128 v[56:59], v179 offset:38912
	ds_read_b128 v[60:63], v179 offset:39936
	global_load_lds_dwordx4 v[172:173], off
	v_lshl_add_u64 v[172:173], s[4:5], 0, v[166:167]
	v_lshl_add_u64 v[172:173], v[172:173], 0, s[6:7]
	s_mov_b32 m0, s37
	s_nop 0
	global_load_lds_dwordx4 v[172:173], off
	s_waitcnt vmcnt(8)
	s_waitcnt lgkmcnt(0)
	s_barrier
	s_setprio 1
	s_waitcnt lgkmcnt(0)
	v_mfma_f32_16x16x128_f8f6f4 v[156:159], v[0:7], v[32:39], v[156:159]
	v_mfma_f32_16x16x128_f8f6f4 v[152:155], v[8:15], v[32:39], v[152:155]
	v_mfma_f32_16x16x128_f8f6f4 v[140:143], v[0:7], v[40:47], v[140:143]
	v_mfma_f32_16x16x128_f8f6f4 v[136:139], v[8:15], v[40:47], v[136:139]
	v_mfma_f32_16x16x128_f8f6f4 v[124:127], v[0:7], v[48:55], v[124:127]
	v_mfma_f32_16x16x128_f8f6f4 v[120:123], v[8:15], v[48:55], v[120:123]
	v_mfma_f32_16x16x128_f8f6f4 v[108:111], v[0:7], v[56:63], v[108:111]
	v_mfma_f32_16x16x128_f8f6f4 v[104:107], v[8:15], v[56:63], v[104:107]
	v_mfma_f32_16x16x128_f8f6f4 v[148:151], v[16:23], v[32:39], v[148:151]
	v_mfma_f32_16x16x128_f8f6f4 v[144:147], v[24:31], v[32:39], v[144:147]
	v_mfma_f32_16x16x128_f8f6f4 v[132:135], v[16:23], v[40:47], v[132:135]
	v_mfma_f32_16x16x128_f8f6f4 v[128:131], v[24:31], v[40:47], v[128:131]
	v_mfma_f32_16x16x128_f8f6f4 v[116:119], v[16:23], v[48:55], v[116:119]
	v_mfma_f32_16x16x128_f8f6f4 v[112:115], v[24:31], v[48:55], v[112:115]
	v_mfma_f32_16x16x128_f8f6f4 v[100:103], v[16:23], v[56:63], v[100:103]
	v_mfma_f32_16x16x128_f8f6f4 v[96:99], v[24:31], v[56:63], v[96:99]
	s_setprio 0
	s_barrier
	s_add_i32 s6, s26, s84
	v_lshl_add_u64 v[40:41], v[232:233], 0, s[10:11]
	s_mov_b32 m0, s6
	ds_read_b128 v[32:35], v179 offset:49152
	ds_read_b128 v[36:39], v179 offset:50176
	ds_read_b128 v[48:51], v179 offset:51200
	ds_read_b128 v[52:55], v179 offset:52224
	ds_read_b128 v[180:183], v179 offset:53248
	ds_read_b128 v[184:187], v179 offset:54272
	ds_read_b128 v[188:191], v179 offset:55296
	ds_read_b128 v[192:195], v179 offset:56320
	global_load_lds_dwordx4 v[40:41], off
	s_add_i32 m0, s6, 0x2000
	s_add_u32 s22, s22, 0x20080
	v_lshl_add_u64 v[40:41], v[234:235], 0, s[10:11]
	s_addc_u32 s23, s23, 0
	s_add_i32 s6, s27, s84
	global_load_lds_dwordx4 v[40:41], off
	v_lshl_add_u64 v[40:41], s[22:23], 0, v[162:163]
	s_mov_b32 m0, s6
	s_nop 0
	global_load_lds_dwordx4 v[40:41], off
	v_lshl_add_u64 v[40:41], s[22:23], 0, v[160:161]
	s_add_i32 m0, s6, 0x2000
	s_nop 0
	global_load_lds_dwordx4 v[40:41], off
	v_lshl_add_u64 v[40:41], v[236:237], 0, s[10:11]
	s_mov_b32 m0, s38
	s_nop 0
	global_load_lds_dwordx4 v[40:41], off
	v_lshl_add_u64 v[40:41], v[238:239], 0, s[10:11]
	s_mov_b32 m0, s39
	s_nop 0
	global_load_lds_dwordx4 v[40:41], off
	s_waitcnt vmcnt(8)
	s_waitcnt lgkmcnt(0)
	s_barrier
	s_setprio 1
	s_waitcnt lgkmcnt(0)
	v_mfma_f32_16x16x128_f8f6f4 v[92:95], v[0:7], v[32:39], v[92:95]
	v_mfma_f32_16x16x128_f8f6f4 v[88:91], v[8:15], v[32:39], v[88:91]
	v_mfma_f32_16x16x128_f8f6f4 v[76:79], v[0:7], v[48:55], v[76:79]
	v_mfma_f32_16x16x128_f8f6f4 v[72:75], v[8:15], v[48:55], v[72:75]
	v_mfma_f32_16x16x128_f8f6f4 v[60:63], v[0:7], v[180:187], v[212:215]
	v_mfma_f32_16x16x128_f8f6f4 v[56:59], v[8:15], v[180:187], v[216:219]
	v_mfma_f32_16x16x128_f8f6f4 v[44:47], v[0:7], v[188:195], v[220:223]
	v_mfma_f32_16x16x128_f8f6f4 v[40:43], v[8:15], v[188:195], v[224:227]
	v_mfma_f32_16x16x128_f8f6f4 v[84:87], v[16:23], v[32:39], v[84:87]
	v_mfma_f32_16x16x128_f8f6f4 v[80:83], v[24:31], v[32:39], v[80:83]
	v_mfma_f32_16x16x128_f8f6f4 v[68:71], v[16:23], v[48:55], v[68:71]
	v_mfma_f32_16x16x128_f8f6f4 v[64:67], v[24:31], v[48:55], v[64:67]
	v_mfma_f32_16x16x128_f8f6f4 v[52:55], v[16:23], v[180:187], v[228:231]
	v_mfma_f32_16x16x128_f8f6f4 v[48:51], v[24:31], v[180:187], v[196:199]
	v_mfma_f32_16x16x128_f8f6f4 v[36:39], v[16:23], v[188:195], v[200:203]
	v_mfma_f32_16x16x128_f8f6f4 v[32:35], v[24:31], v[188:195], v[204:207]
	s_setprio 0
	s_barrier
	s_add_i32 s57, s57, 2
	s_cmp_gt_u32 s57, 5
	s_cbranch_scc1 .LBB0_1253
	s_mov_b64 s[22:23], s[24:25]
	s_branch .LBB0_1248

.LBB0_1324:
	ds_read_b128 v[16:19], v175
	ds_read_b128 v[20:23], v175 offset:1024
	ds_read_b128 v[24:27], v175 offset:2048
	ds_read_b128 v[28:31], v175 offset:3072
	ds_read_b128 v[0:3], v176
	ds_read_b128 v[4:7], v176 offset:1024
	ds_read_b128 v[8:11], v176 offset:2048
	ds_read_b128 v[12:15], v176 offset:3072
	s_cmp_eq_u32 s52, 18
	s_cselect_b64 s[22:23], -1, 0
	s_add_u32 s20, s38, s18
	s_addc_u32 s21, s39, s19
	s_mov_b32 m0, s40
	ds_read_b128 v[178:181], v177
	ds_read_b128 v[182:185], v177 offset:1024
	ds_read_b128 v[186:189], v177 offset:2048
	ds_read_b128 v[190:193], v177 offset:3072
	ds_read_b128 v[194:197], v177 offset:4096
	ds_read_b128 v[198:201], v177 offset:5120
	ds_read_b128 v[202:205], v177 offset:6144
	ds_read_b128 v[206:209], v177 offset:7168
	global_load_lds_dwordx4 v166, s[20:21]
	s_mov_b32 m0, s41
	s_nop 0
	global_load_lds_dwordx4 v170, s[20:21]
	s_waitcnt vmcnt(8)
	s_waitcnt lgkmcnt(0)
	s_barrier
	s_setprio 1
	s_waitcnt lgkmcnt(0)
	v_mfma_f32_16x16x128_f8f6f4 v[156:159], v[16:23], v[178:185], v[156:159]
	v_mfma_f32_16x16x128_f8f6f4 v[152:155], v[24:31], v[178:185], v[152:155]
	v_mfma_f32_16x16x128_f8f6f4 v[140:143], v[16:23], v[186:193], v[140:143]
	v_mfma_f32_16x16x128_f8f6f4 v[136:139], v[24:31], v[186:193], v[136:139]
	v_mfma_f32_16x16x128_f8f6f4 v[124:127], v[16:23], v[194:201], v[124:127]
	v_mfma_f32_16x16x128_f8f6f4 v[120:123], v[24:31], v[194:201], v[120:123]
	v_mfma_f32_16x16x128_f8f6f4 v[108:111], v[16:23], v[202:209], v[108:111]
	v_mfma_f32_16x16x128_f8f6f4 v[104:107], v[24:31], v[202:209], v[104:107]
	v_mfma_f32_16x16x128_f8f6f4 v[148:151], v[0:7], v[178:185], v[148:151]
	v_mfma_f32_16x16x128_f8f6f4 v[144:147], v[8:15], v[178:185], v[144:147]
	v_mfma_f32_16x16x128_f8f6f4 v[132:135], v[0:7], v[186:193], v[132:135]
	v_mfma_f32_16x16x128_f8f6f4 v[128:131], v[8:15], v[186:193], v[128:131]
	v_mfma_f32_16x16x128_f8f6f4 v[116:119], v[0:7], v[194:201], v[116:119]
	v_mfma_f32_16x16x128_f8f6f4 v[112:115], v[8:15], v[194:201], v[112:115]
	v_mfma_f32_16x16x128_f8f6f4 v[100:103], v[0:7], v[202:209], v[100:103]
	v_mfma_f32_16x16x128_f8f6f4 v[96:99], v[8:15], v[202:209], v[96:99]
	s_setprio 0
	s_barrier
	s_and_b64 s[20:21], s[16:17], s[22:23]
	s_andn2_b64 vcc, exec, s[20:21]
	s_cbranch_vccnz .LBB0_1326
	v_mov_b32_e32 v164, v174
	s_nop 0
	v_add_u32_e32 v164, s33, v164
	v_ashrrev_i32_e32 v167, 31, v164
	v_lshrrev_b32_e32 v167, 26, v167
	v_lshlrev_b32_e32 v166, 4, v164
	v_add_u32_e32 v167, v164, v167
	v_bfe_i32 v164, v164, 27, 1
	v_lshrrev_b32_e32 v164, 22, v164
	v_add_u32_e32 v164, v166, v164
	v_and_b32_e32 v164, 0xfffffc00, v164
	v_sub_u32_e32 v164, v166, v164
	v_lshrrev_b32_e32 v168, 4, v164
	v_bitop3_b32 v164, v168, v164, 32 bitop3:0x6c
	v_ashrrev_i32_e32 v169, 31, v164
	v_ashrrev_i32_e32 v167, 6, v167
	v_lshrrev_b32_e32 v169, 26, v169
	v_lshlrev_b32_e32 v168, 3, v167
	v_add_u32_e32 v169, v164, v169
	v_and_b32_e32 v168, -16, v168
	v_ashrrev_i32_e32 v170, 6, v169
	v_add_u32_e32 v171, v170, v168
	v_and_b32_e32 v168, 0xc0, v169
	v_add_u32_e32 v166, 0x2000, v166
	v_sub_u32_e32 v164, v164, v168
	v_ashrrev_i32_e32 v168, 31, v166
	v_lshrrev_b32_e32 v168, 22, v168
	v_add_u32_e32 v168, v166, v168
	v_ashrrev_i32_e32 v168, 10, v168
	v_mul_i32_i24_e32 v169, 0x400, v168
	v_sub_u32_e32 v166, v166, v169
	v_lshrrev_b32_e32 v169, 4, v166
	v_bitop3_b32 v166, v169, v166, 32 bitop3:0x6c
	v_ashrrev_i32_e32 v170, 31, v166
	v_lshrrev_b32_e32 v170, 26, v170
	v_lshlrev_b32_e32 v169, 3, v168
	v_add_u32_e32 v170, v166, v170
	v_and_b32_e32 v169, -16, v169
	v_ashrrev_i32_e32 v178, 6, v170
	v_add_u32_e32 v180, v178, v169
	v_and_b32_e32 v169, 0xc0, v170
	v_sub_u32_e32 v166, v166, v169
	v_lshlrev_b32_e32 v167, 5, v167
	v_ashrrev_i16_sdwa v164, v172, sext(v164) dst_sel:DWORD dst_unused:UNUSED_PAD src0_sel:DWORD src1_sel:BYTE_0
	v_lshlrev_b32_e32 v168, 5, v168
	v_ashrrev_i16_sdwa v166, v172, sext(v166) dst_sel:DWORD dst_unused:UNUSED_PAD src0_sel:DWORD src1_sel:BYTE_0
	v_and_b32_e32 v167, 32, v167
	v_bfe_i32 v164, v164, 0, 16
	v_and_b32_e32 v168, 32, v168
	v_bfe_i32 v166, v166, 0, 16
	v_add_u32_e32 v169, s48, v171
	v_add_lshl_u32 v164, v167, v164, 1
	v_add_u32_e32 v167, s48, v180
	v_add_lshl_u32 v170, v168, v166, 1
	v_add_u32_e32 v166, s49, v171
	v_mad_u64_u32 v[178:179], s[20:21], v169, s28, v[164:165]
	v_mad_u64_u32 v[168:169], s[20:21], v167, s28, v[170:171]
	v_mad_u64_u32 v[166:167], s[20:21], v166, s28, v[164:165]
	v_add_u32_e32 v164, s49, v180
	v_mad_u64_u32 v[170:171], s[20:21], v164, s28, v[170:171]
	v_mov_b32_e32 v167, v165
	v_mov_b32_e32 v171, v165
	v_mov_b32_e32 v164, v178
	s_branch .LBB0_1327

.LBB0_1327:
	s_add_u32 s20, s18, 0x100
	s_addc_u32 s21, s19, 0
	s_and_b64 s[56:57], s[22:23], exec
	s_cselect_b32 s4, 0, s20
	s_add_u32 s53, s50, s18
	s_addc_u32 s56, s51, s19
	s_and_b64 s[18:19], s[22:23], exec
	s_cselect_b32 s19, s15, s56
	s_cselect_b32 s18, s14, s53
	s_mov_b32 m0, s26
	v_lshl_add_u64 v[230:231], s[18:19], 0, v[162:163]
	s_add_u32 s22, s18, 0x58000
	ds_read_b128 v[178:181], v177 offset:16384
	ds_read_b128 v[182:185], v177 offset:17408
	ds_read_b128 v[186:189], v177 offset:18432
	ds_read_b128 v[190:193], v177 offset:19456
	ds_read_b128 v[194:197], v177 offset:20480
	ds_read_b128 v[198:201], v177 offset:21504
	ds_read_b128 v[202:205], v177 offset:22528
	ds_read_b128 v[206:209], v177 offset:23552
	global_load_lds_dwordx4 v[230:231], off
	v_lshl_add_u64 v[232:233], s[18:19], 0, v[160:161]
	s_mov_b32 m0, s27
	s_addc_u32 s23, s19, 0
	global_load_lds_dwordx4 v[232:233], off
	v_lshl_add_u64 v[210:211], s[22:23], 0, v[162:163]
	s_mov_b32 m0, s29
	v_mov_b32_e32 v169, v165
	global_load_lds_dwordx4 v[210:211], off
	v_lshl_add_u64 v[210:211], s[22:23], 0, v[160:161]
	s_mov_b32 m0, s30
	s_nop 0
	global_load_lds_dwordx4 v[210:211], off
	v_lshl_add_u64 v[210:211], s[2:3], 0, v[164:165]
	v_lshl_add_u64 v[234:235], v[210:211], 0, s[4:5]
	s_mov_b32 m0, s25
	v_lshl_add_u64 v[210:211], s[2:3], 0, v[168:169]
	global_load_lds_dwordx4 v[234:235], off
	v_lshl_add_u64 v[236:237], v[210:211], 0, s[4:5]
	s_mov_b32 m0, s31
	s_nop 0
	global_load_lds_dwordx4 v[236:237], off
	s_waitcnt vmcnt(8)
	s_waitcnt lgkmcnt(0)
	s_barrier
	s_setprio 1
	s_waitcnt lgkmcnt(0)
	v_mfma_f32_16x16x128_f8f6f4 v[92:95], v[16:23], v[178:185], v[92:95]
	v_mfma_f32_16x16x128_f8f6f4 v[88:91], v[24:31], v[178:185], v[88:91]
	v_mfma_f32_16x16x128_f8f6f4 v[76:79], v[16:23], v[186:193], v[76:79]
	v_mfma_f32_16x16x128_f8f6f4 v[72:75], v[24:31], v[186:193], v[72:75]
	v_mfma_f32_16x16x128_f8f6f4 v[210:213], v[16:23], v[194:201], v[60:63]
	v_mfma_f32_16x16x128_f8f6f4 v[214:217], v[24:31], v[194:201], v[56:59]
	v_mfma_f32_16x16x128_f8f6f4 v[218:221], v[16:23], v[202:209], v[44:47]
	v_mfma_f32_16x16x128_f8f6f4 v[222:225], v[24:31], v[202:209], v[40:43]
	v_mfma_f32_16x16x128_f8f6f4 v[84:87], v[0:7], v[178:185], v[84:87]
	v_mfma_f32_16x16x128_f8f6f4 v[80:83], v[8:15], v[178:185], v[80:83]
	v_mfma_f32_16x16x128_f8f6f4 v[68:71], v[0:7], v[186:193], v[68:71]
	v_mfma_f32_16x16x128_f8f6f4 v[64:67], v[8:15], v[186:193], v[64:67]
	v_mfma_f32_16x16x128_f8f6f4 v[226:229], v[0:7], v[194:201], v[52:55]
	v_mfma_f32_16x16x128_f8f6f4 v[194:197], v[8:15], v[194:201], v[48:51]
	v_mfma_f32_16x16x128_f8f6f4 v[198:201], v[0:7], v[202:209], v[36:39]
	v_mfma_f32_16x16x128_f8f6f4 v[202:205], v[8:15], v[202:209], v[32:35]
	s_setprio 0
	s_barrier
	s_add_i32 s22, 0, 0x18000
	s_add_i32 s23, 0, 0x1c000
	v_add_u32_e32 v12, s22, v173
	v_add_u32_e32 v28, s23, v173
	ds_read_b128 v[0:3], v12
	ds_read_b128 v[4:7], v12 offset:1024
	ds_read_b128 v[8:11], v12 offset:2048
	ds_read_b128 v[12:15], v12 offset:3072
	ds_read_b128 v[16:19], v28
	ds_read_b128 v[20:23], v28 offset:1024
	ds_read_b128 v[24:27], v28 offset:2048
	ds_read_b128 v[28:31], v28 offset:3072
	v_lshl_add_u64 v[178:179], s[2:3], 0, v[166:167]
	s_mov_b32 m0, s34
	v_lshl_add_u64 v[178:179], v[178:179], 0, s[4:5]
	ds_read_b128 v[32:35], v177 offset:32768
	ds_read_b128 v[36:39], v177 offset:33792
	ds_read_b128 v[40:43], v177 offset:34816
	ds_read_b128 v[44:47], v177 offset:35840
	ds_read_b128 v[48:51], v177 offset:36864
	ds_read_b128 v[52:55], v177 offset:37888
	ds_read_b128 v[56:59], v177 offset:38912
	ds_read_b128 v[60:63], v177 offset:39936
	global_load_lds_dwordx4 v[178:179], off
	v_lshl_add_u64 v[178:179], s[2:3], 0, v[170:171]
	v_lshl_add_u64 v[178:179], v[178:179], 0, s[4:5]
	s_mov_b32 m0, s35
	s_nop 0
	global_load_lds_dwordx4 v[178:179], off
	s_waitcnt vmcnt(8)
	s_waitcnt lgkmcnt(0)
	s_barrier
	s_setprio 1
	s_waitcnt lgkmcnt(0)
	v_mfma_f32_16x16x128_f8f6f4 v[156:159], v[0:7], v[32:39], v[156:159]
	v_mfma_f32_16x16x128_f8f6f4 v[152:155], v[8:15], v[32:39], v[152:155]
	v_mfma_f32_16x16x128_f8f6f4 v[140:143], v[0:7], v[40:47], v[140:143]
	v_mfma_f32_16x16x128_f8f6f4 v[136:139], v[8:15], v[40:47], v[136:139]
	v_mfma_f32_16x16x128_f8f6f4 v[124:127], v[0:7], v[48:55], v[124:127]
	v_mfma_f32_16x16x128_f8f6f4 v[120:123], v[8:15], v[48:55], v[120:123]
	v_mfma_f32_16x16x128_f8f6f4 v[108:111], v[0:7], v[56:63], v[108:111]
	v_mfma_f32_16x16x128_f8f6f4 v[104:107], v[8:15], v[56:63], v[104:107]
	v_mfma_f32_16x16x128_f8f6f4 v[148:151], v[16:23], v[32:39], v[148:151]
	v_mfma_f32_16x16x128_f8f6f4 v[144:147], v[24:31], v[32:39], v[144:147]
	v_mfma_f32_16x16x128_f8f6f4 v[132:135], v[16:23], v[40:47], v[132:135]
	v_mfma_f32_16x16x128_f8f6f4 v[128:131], v[24:31], v[40:47], v[128:131]
	v_mfma_f32_16x16x128_f8f6f4 v[116:119], v[16:23], v[48:55], v[116:119]
	v_mfma_f32_16x16x128_f8f6f4 v[112:115], v[24:31], v[48:55], v[112:115]
	v_mfma_f32_16x16x128_f8f6f4 v[100:103], v[16:23], v[56:63], v[100:103]
	v_mfma_f32_16x16x128_f8f6f4 v[96:99], v[24:31], v[56:63], v[96:99]
	s_setprio 0
	s_barrier
	s_add_i32 s4, s22, s84
	v_lshl_add_u64 v[40:41], v[230:231], 0, s[10:11]
	s_mov_b32 m0, s4
	ds_read_b128 v[32:35], v177 offset:49152
	ds_read_b128 v[36:39], v177 offset:50176
	ds_read_b128 v[48:51], v177 offset:51200
	ds_read_b128 v[52:55], v177 offset:52224
	ds_read_b128 v[178:181], v177 offset:53248
	ds_read_b128 v[182:185], v177 offset:54272
	ds_read_b128 v[186:189], v177 offset:55296
	ds_read_b128 v[190:193], v177 offset:56320
	global_load_lds_dwordx4 v[40:41], off
	s_add_i32 m0, s4, 0x2000
	s_add_u32 s18, s18, 0x58080
	v_lshl_add_u64 v[40:41], v[232:233], 0, s[10:11]
	s_addc_u32 s19, s19, 0
	s_add_i32 s4, s23, s84
	global_load_lds_dwordx4 v[40:41], off
	v_lshl_add_u64 v[40:41], s[18:19], 0, v[162:163]
	s_mov_b32 m0, s4
	s_nop 0
	global_load_lds_dwordx4 v[40:41], off
	v_lshl_add_u64 v[40:41], s[18:19], 0, v[160:161]
	s_add_i32 m0, s4, 0x2000
	s_nop 0
	global_load_lds_dwordx4 v[40:41], off
	v_lshl_add_u64 v[40:41], v[234:235], 0, s[10:11]
	s_mov_b32 m0, s36
	s_nop 0
	global_load_lds_dwordx4 v[40:41], off
	v_lshl_add_u64 v[40:41], v[236:237], 0, s[10:11]
	s_mov_b32 m0, s37
	s_nop 0
	global_load_lds_dwordx4 v[40:41], off
	s_waitcnt vmcnt(8)
	s_waitcnt lgkmcnt(0)
	s_barrier
	s_setprio 1
	s_waitcnt lgkmcnt(0)
	v_mfma_f32_16x16x128_f8f6f4 v[92:95], v[0:7], v[32:39], v[92:95]
	v_mfma_f32_16x16x128_f8f6f4 v[88:91], v[8:15], v[32:39], v[88:91]
	v_mfma_f32_16x16x128_f8f6f4 v[76:79], v[0:7], v[48:55], v[76:79]
	v_mfma_f32_16x16x128_f8f6f4 v[72:75], v[8:15], v[48:55], v[72:75]
	v_mfma_f32_16x16x128_f8f6f4 v[60:63], v[0:7], v[178:185], v[210:213]
	v_mfma_f32_16x16x128_f8f6f4 v[56:59], v[8:15], v[178:185], v[214:217]
	v_mfma_f32_16x16x128_f8f6f4 v[44:47], v[0:7], v[186:193], v[218:221]
	v_mfma_f32_16x16x128_f8f6f4 v[40:43], v[8:15], v[186:193], v[222:225]
	v_mfma_f32_16x16x128_f8f6f4 v[84:87], v[16:23], v[32:39], v[84:87]
	v_mfma_f32_16x16x128_f8f6f4 v[80:83], v[24:31], v[32:39], v[80:83]
	v_mfma_f32_16x16x128_f8f6f4 v[68:71], v[16:23], v[48:55], v[68:71]
	v_mfma_f32_16x16x128_f8f6f4 v[64:67], v[24:31], v[48:55], v[64:67]
	v_mfma_f32_16x16x128_f8f6f4 v[52:55], v[16:23], v[178:185], v[226:229]
	v_mfma_f32_16x16x128_f8f6f4 v[48:51], v[24:31], v[178:185], v[194:197]
	v_mfma_f32_16x16x128_f8f6f4 v[36:39], v[16:23], v[186:193], v[198:201]
	v_mfma_f32_16x16x128_f8f6f4 v[32:35], v[24:31], v[186:193], v[202:205]
	s_setprio 0
	s_barrier
	s_add_i32 s52, s52, 2
	s_cmp_gt_u32 s52, 19
	s_cbranch_scc1 .LBB0_1329
	s_mov_b64 s[18:19], s[20:21]
	s_branch .LBB0_1324
